# final RMSNorm: loop-invariant final_g loads hoisted out of the row loop
# speedup vs baseline: 1.0145x; 1.0019x over previous
; __device__ __forceinline__ int tid_() { int t = threadIdx.x; asm volatile("" : "+v"(t)); return t; }
; __device__ __forceinline__ int bid_() { int t = blockIdx.x; asm volatile("" : "+s"(t)); return t; }
; __device__ __forceinline__ int nblk_() { int t = gridDim.x; asm volatile("" : "+s"(t)); return t; }
; __device__ __forceinline__ void final_norm(KArgs& a) {
;     const int lane = tid_() & 63, gw = bid_() * 8 + (tid_() >> 6), ngw = nblk_() * 8;
;     for (int r = gw; r < NB * SEQ; r += ngw) {
;         float* xr = a.out + (size_t)r * DM; f32x4 v[4]; float s = 0.f;
; #pragma unroll
;         for (int j = 0; j < 4; ++j) { v[j] = ((const f32x4*)xr)[lane + 64 * j]; s += (v[j].x * v[j].x + v[j].y * v[j].y) + (v[j].z * v[j].z + v[j].w * v[j].w); }
;         const float rstd = rsqrtf(wave_sum(s) * (1.f / DM) + 1e-6f);
; #pragma unroll
;         for (int j = 0; j < 4; ++j) ((f32x4*)xr)[lane + 64 * j] = v[j] * rstd * ((const f32x4*)a.final_g)[lane + 64 * j];
;     }
.LBB0_1475:
	s_cmp_lt_i32 s50, 42
	s_cselect_b64 s[0:1], -1, 0
	s_cmp_gt_i32 s51, 41
	s_cselect_b64 s[2:3], -1, 0
	s_and_b64 s[0:1], s[0:1], s[2:3]
	s_and_b64 vcc, exec, s[0:1]
	s_cbranch_vccz .LBB0_1533
	v_readlane_b32 s10, v237, 2
	v_readlane_b32 s11, v237, 3
	s_mov_b32 s0, 0
	v_readlane_b32 s8, v237, 4
	s_mov_b32 s0, s84
	s_mov_b32 s1, s8
	v_mov_b32_e32 v1, v216
	s_mov_b32 s0, 0x8000
	v_ashrrev_i32_e32 v0, 6, v216
	v_lshl_add_u32 v0, s84, 3, v0
	v_cmp_gt_i32_e32 vcc, s0, v0
	v_readlane_b32 s9, v237, 5
	s_and_saveexec_b64 s[0:1], vcc
	s_cbranch_execz .LBB0_1479
	v_and_b32_e32 v2, 64, v217
	v_add_u32_e32 v2, 64, v2
	v_xor_b32_e32 v3, 1, v217
	v_cmp_lt_i32_e32 vcc, v3, v2
	s_load_dwordx4 s[4:7], s[10:11], 0xd0
	v_lshlrev_b32_e32 v1, 4, v1
	v_cndmask_b32_e32 v3, v217, v3, vcc
	v_lshlrev_b32_e32 v6, 2, v3
	v_xor_b32_e32 v3, 2, v217
	v_cmp_lt_i32_e32 vcc, v3, v2
	v_and_b32_e32 v4, 0x3f0, v1
	v_ashrrev_i32_e32 v1, 31, v0
	v_cndmask_b32_e32 v3, v217, v3, vcc
	v_lshlrev_b32_e32 v7, 2, v3
	v_xor_b32_e32 v3, 4, v217
	v_cmp_lt_i32_e32 vcc, v3, v2
	v_lshlrev_b64 v[12:13], 12, v[0:1]
	s_lshl_b32 s2, s8, 3
	v_cndmask_b32_e32 v3, v217, v3, vcc
	v_lshlrev_b32_e32 v8, 2, v3
	v_xor_b32_e32 v3, 8, v217
	v_cmp_lt_i32_e32 vcc, v3, v2
	v_mov_b32_e32 v5, 0
	v_or_b32_e32 v12, v12, v4
	v_cndmask_b32_e32 v3, v217, v3, vcc
	v_lshlrev_b32_e32 v9, 2, v3
	v_xor_b32_e32 v3, 16, v217
	v_cmp_lt_i32_e32 vcc, v3, v2
	s_ashr_i32 s3, s2, 31
	v_mov_b32_e32 v1, 0x358637bd
	v_cndmask_b32_e32 v3, v217, v3, vcc
	v_lshlrev_b32_e32 v10, 2, v3
	v_xor_b32_e32 v3, 32, v217
	v_cmp_lt_i32_e32 vcc, v3, v2
	s_movk_i32 s8, 0x7fff
	s_nop 0
	v_cndmask_b32_e32 v2, v217, v3, vcc
	v_lshlrev_b32_e32 v11, 2, v2
	s_waitcnt lgkmcnt(0)
	v_lshl_add_u64 v[2:3], s[4:5], 0, v[4:5]
	v_lshl_add_u64 v[4:5], s[6:7], 0, v[12:13]
	s_mov_b64 s[4:5], 0xc00
	v_lshl_add_u64 v[4:5], v[4:5], 0, s[4:5]
	s_lshl_b64 s[4:5], s[2:3], 12
	s_mov_b64 s[6:7], 0
	s_mov_b32 s3, 0x800000
	global_load_dwordx4 v[148:151], v[2:3], off
	global_load_dwordx4 v[152:155], v[2:3], off offset:1024
	global_load_dwordx4 v[156:159], v[2:3], off offset:2048
	global_load_dwordx4 v[160:163], v[2:3], off offset:3072
	s_waitcnt vmcnt(0)
.LBB0_1478:
	global_load_dwordx4 v[12:15], v[4:5], off offset:-3072
	global_load_dwordx4 v[16:19], v[4:5], off offset:-2048
	global_load_dwordx4 v[20:23], v[4:5], off
	global_load_dwordx4 v[24:27], v[4:5], off offset:-1024
	v_add_u32_e32 v0, s2, v0
	s_waitcnt vmcnt(0)
	v_pk_mul_f32 v[32:33], v[14:15], v[14:15]
	v_pk_mul_f32 v[34:35], v[12:13], v[12:13]
	v_pk_mul_f32 v[36:37], v[18:19], v[18:19]
	v_pk_mul_f32 v[38:39], v[16:17], v[16:17]
	v_pk_mov_b32 v[44:45], v[34:35], v[32:33] op_sel:[1,0]
	v_mov_b32_e32 v35, v33
	v_pk_mov_b32 v[32:33], v[38:39], v[36:37] op_sel:[1,0]
	v_mov_b32_e32 v39, v37
	v_mul_f32_e32 v43, v20, v20
	v_mul_f32_e32 v40, v25, v25
	v_mul_f32_e32 v42, v27, v27
	v_pk_add_f32 v[34:35], v[44:45], v[34:35]
	v_pk_add_f32 v[32:33], v[32:33], v[38:39]
	v_mul_f32_e32 v46, v21, v21
	v_mul_f32_e32 v47, v22, v22
	v_mul_f32_e32 v48, v23, v23
	v_pk_fma_f32 v[36:37], v[24:25], v[24:25], v[40:41] op_sel_hi:[1,1,0]
	v_pk_fma_f32 v[40:41], v[26:27], v[26:27], v[42:43] op_sel_hi:[1,1,0]
	v_pk_add_f32 v[34:35], v[34:35], v[34:35] op_sel:[0,1] op_sel_hi:[1,0]
	v_pk_add_f32 v[32:33], v[32:33], v[32:33] op_sel:[0,1] op_sel_hi:[1,0]
	v_mov_b32_e32 v37, v47
	v_mov_b32_e32 v41, v48
	v_mov_b32_e32 v35, v43
	v_mov_b32_e32 v33, v46
	v_pk_add_f32 v[36:37], v[36:37], v[40:41]
	v_pk_add_f32 v[32:33], v[34:35], v[32:33]
	s_nop 0
	v_pk_add_f32 v[32:33], v[32:33], v[36:37]
	s_nop 0
	v_add_f32_e32 v32, v32, v33
	ds_bpermute_b32 v33, v6, v32
	s_waitcnt lgkmcnt(0)
	v_add_f32_e32 v32, v32, v33
	ds_bpermute_b32 v33, v7, v32
	s_waitcnt lgkmcnt(0)
	v_add_f32_e32 v32, v32, v33
	ds_bpermute_b32 v33, v8, v32
	s_waitcnt lgkmcnt(0)
	v_add_f32_e32 v32, v32, v33
	ds_bpermute_b32 v33, v9, v32
	s_waitcnt lgkmcnt(0)
	v_add_f32_e32 v32, v32, v33
	ds_bpermute_b32 v33, v10, v32
	s_waitcnt lgkmcnt(0)
	v_add_f32_e32 v32, v32, v33
	ds_bpermute_b32 v33, v11, v32
	s_waitcnt lgkmcnt(0)
	v_add_f32_e32 v32, v32, v33
	v_fmamk_f32 v32, v32, 0x3a800000, v1
	v_mul_f32_e32 v33, 0x4b800000, v32
	v_cmp_gt_f32_e32 vcc, s3, v32
	s_nop 1
	v_cndmask_b32_e32 v32, v32, v33, vcc
	v_rsq_f32_e32 v32, v32
	s_nop 0
	v_mul_f32_e32 v33, 0x45800000, v32
	v_cndmask_b32_e32 v32, v32, v33, vcc
	v_pk_mul_f32 v[12:13], v[12:13], v[32:33] op_sel_hi:[1,0]
	v_pk_mul_f32 v[14:15], v[14:15], v[32:33] op_sel_hi:[1,0]
	v_pk_mul_f32 v[12:13], v[148:149], v[12:13]
	v_pk_mul_f32 v[14:15], v[150:151], v[14:15]
	global_store_dwordx4 v[4:5], v[12:15], off offset:-3072
	v_pk_mul_f32 v[18:19], v[18:19], v[32:33] op_sel_hi:[1,0]
	v_pk_mul_f32 v[16:17], v[16:17], v[32:33] op_sel_hi:[1,0]
	v_cmp_lt_i32_e32 vcc, s8, v0
	s_or_b64 s[6:7], vcc, s[6:7]
	v_pk_mul_f32 v[12:13], v[152:153], v[16:17]
	v_pk_mul_f32 v[14:15], v[154:155], v[18:19]
	global_store_dwordx4 v[4:5], v[12:15], off offset:-2048
	v_pk_mul_f32 v[16:17], v[26:27], v[32:33] op_sel_hi:[1,0]
	v_pk_mul_f32 v[18:19], v[24:25], v[32:33] op_sel_hi:[1,0]
	v_pk_mul_f32 v[14:15], v[158:159], v[16:17]
	v_pk_mul_f32 v[12:13], v[156:157], v[18:19]
	global_store_dwordx4 v[4:5], v[12:15], off offset:-1024
	v_pk_mul_f32 v[16:17], v[22:23], v[32:33] op_sel_hi:[1,0]
	v_pk_mul_f32 v[18:19], v[20:21], v[32:33] op_sel_hi:[1,0]
	v_pk_mul_f32 v[14:15], v[162:163], v[16:17]
	v_pk_mul_f32 v[12:13], v[160:161], v[18:19]
	global_store_dwordx4 v[4:5], v[12:15], off
	v_lshl_add_u64 v[4:5], v[4:5], 0, s[4:5]
	s_andn2_b64 exec, exec, s[6:7]
	s_cbranch_execnz .LBB0_1478
